# GLA state publish: device-scope write-through stores (sc1) + vmcnt(0) instead of a full L2 writeback (buffer_wbl2) before the flag
# speedup vs baseline: 1.0130x; 1.0108x over previous
; #define LAS __attribute__((address_space(3)))
; template <bool FULL>
; __device__ __forceinline__ void gla_pass(const Params& P, LAS unsigned char* lds, f32x4 (&S)[8][2], int bh, int c0, int L, bool dry) {
;     ...
;         for (int kt = 0; kt < 8; ++kt) { const f32x4 dv = *(const LAS f32x4*)(Ldec + 16 * kt + 4 * g); S[kt][0] = S[kt][0] * dv; S[kt][1] = S[kt][1] * dv; }
; #pragma unroll
;         for (int k2 = 0; k2 < 2; ++k2)
; #pragma unroll
;             for (int kt = 0; kt < 8; ++kt) { const bf16x8 ak = trfrag(Lks, KS_P, 32 * k2, 32 * kt, g, fr);
;                 S[kt][0] = __builtin_amdgcn_mfma_f32_16x16x32_bf16(ak, vf[0][k2], S[kt][0], 0, 0, 0); S[kt][1] = __builtin_amdgcn_mfma_f32_16x16x32_bf16(ak, vf[1][k2], S[kt][1], 0, 0, 0); }
; __device__ __forceinline__ void gla_scan(const Params& P, LAS unsigned char* lds, int bh, int seg, int nseg, bool dry) {
;     ...
;         char* dst = (char*)(SL + (size_t)(bh * 3 + seg) * 32768);
; #pragma unroll
;         for (int kt = 0; kt < 8; ++kt)
; #pragma unroll
;             for (int vt = 0; vt < 2; ++vt) *(f32x4*)(dst + (size_t)((unsigned)tid * 16u + (unsigned)((kt * 2 + vt) * 8192))) = S[kt][vt];
;         if (tid < 32) {
;             f32x4 dc = (f32x4){1.f, 1.f, 1.f, 1.f};
;             for (int n = c0; n < c0 + L; ++n) dc = dc * *(const f32x4*)(DEC + (size_t)(bh * 64 + n) * 128 + 4 * tid);
;             *(f32x4*)(DL + (size_t)(bh * 4 + seg) * 128 + 4 * tid) = dc;
.LBB0_668:
	v_add_u32_e32 v100, 0x25000, v121
	s_waitcnt vmcnt(3)
	ds_read_b128 v[32:35], v100
	ds_read_b64_tr_b16 v[30:31], v116 offset:38016
	ds_read_b64_tr_b16 v[28:29], v116 offset:35840
	ds_read_b64_tr_b16 v[22:23], v116 offset:38048
	ds_read_b64_tr_b16 v[20:21], v116 offset:35872
	s_waitcnt vmcnt(2)
	ds_read_b128 v[40:43], v100 offset:64
	s_waitcnt vmcnt(0)
	ds_read_b64_tr_b16 v[50:51], v115 offset:1152
	ds_read_b64_tr_b16 v[48:49], v115
	s_waitcnt lgkmcnt(7)
	v_pk_mul_f32 v[46:47], v[90:91], v[34:35]
	v_pk_mul_f32 v[44:45], v[88:89], v[32:33]
	v_pk_mul_f32 v[34:35], v[86:87], v[34:35]
	ds_read_b64_tr_b16 v[52:53], v115 offset:32
	ds_read_b64_tr_b16 v[86:87], v115 offset:64
	ds_read_b64_tr_b16 v[90:91], v115 offset:96
	ds_read_b64_tr_b16 v[54:55], v115 offset:1184
	ds_read_b64_tr_b16 v[88:89], v115 offset:1216
	ds_read_b64_tr_b16 v[92:93], v115 offset:1248
	v_pk_mul_f32 v[32:33], v[84:85], v[32:33]
	s_waitcnt lgkmcnt(6)
	v_mfma_f32_16x16x32_bf16 v[44:47], v[48:51], v[28:31], v[44:47]
	v_mul_f32_e64 v82, v82, v42
	v_mul_f32_e64 v83, v83, v43
	v_pk_mul_f32 v[80:81], v[80:81], v[40:41]
	v_pk_mul_f32 v[42:43], v[78:79], v[42:43]
	v_mfma_f32_16x16x32_bf16 v[32:35], v[48:51], v[20:23], v[32:35]
	ds_read_b128 v[48:51], v100 offset:128
	v_pk_mul_f32 v[40:41], v[76:77], v[40:41]
	s_mul_i32 s4, s1, 3
	s_waitcnt lgkmcnt(3)
	v_mfma_f32_16x16x32_bf16 v[76:79], v[52:55], v[28:31], v[80:83]
	s_add_i32 s4, s4, s3
	s_lshl_b32 s4, s4, 17
	s_add_u32 s4, s18, s4
	ds_read_b128 v[80:83], v100 offset:192
	s_waitcnt lgkmcnt(1)
	v_pk_mul_f32 v[74:75], v[74:75], v[50:51]
	v_pk_mul_f32 v[72:73], v[72:73], v[48:49]
	v_mfma_f32_16x16x32_bf16 v[40:43], v[52:55], v[20:23], v[40:43]
	v_mul_f32_e64 v50, v70, v50
	v_mul_f32_e64 v51, v71, v51
	v_pk_mul_f32 v[48:49], v[68:69], v[48:49]
	s_waitcnt lgkmcnt(0)
	v_pk_mul_f32 v[54:55], v[66:67], v[82:83]
	v_mfma_f32_16x16x32_bf16 v[66:69], v[86:89], v[28:31], v[72:75]
	v_mul_f32_e64 v52, v64, v80
	v_mul_f32_e64 v53, v65, v81
	v_pk_mul_f32 v[58:59], v[58:59], v[82:83]
	v_pk_mul_f32 v[56:57], v[56:57], v[80:81]
	ds_read_b128 v[70:73], v100 offset:256
	ds_read_b128 v[80:83], v100 offset:320
	v_mfma_f32_16x16x32_bf16 v[48:51], v[86:89], v[20:23], v[48:51]
	ds_read_b64_tr_b16 v[84:85], v115 offset:128
	ds_read_b64_tr_b16 v[86:87], v115 offset:1280
	s_addc_u32 s5, s19, 0
	s_waitcnt lgkmcnt(3)
	v_pk_mul_f32 v[62:63], v[62:63], v[72:73]
	v_mfma_f32_16x16x32_bf16 v[52:55], v[90:93], v[28:31], v[52:55]
	v_mul_f32_e64 v60, v60, v70
	v_mul_f32_e64 v61, v61, v71
	v_pk_mul_f32 v[38:39], v[38:39], v[72:73]
	v_pk_mul_f32 v[36:37], v[36:37], v[70:71]
	v_mfma_f32_16x16x32_bf16 v[56:59], v[90:93], v[20:23], v[56:59]
	ds_read_b64_tr_b16 v[88:89], v115 offset:160
	ds_read_b64_tr_b16 v[92:93], v115 offset:192
	ds_read_b64_tr_b16 v[96:97], v115 offset:224
	ds_read_b64_tr_b16 v[90:91], v115 offset:1312
	ds_read_b64_tr_b16 v[94:95], v115 offset:1344
	ds_read_b64_tr_b16 v[98:99], v115 offset:1376
	s_waitcnt lgkmcnt(8)
	v_pk_mul_f32 v[26:27], v[26:27], v[82:83]
	v_pk_mul_f32 v[24:25], v[24:25], v[80:81]
	ds_read_b128 v[70:73], v100 offset:384
	v_pk_mul_f32 v[18:19], v[18:19], v[82:83]
	v_pk_mul_f32 v[16:17], v[16:17], v[80:81]
	ds_read_b128 v[80:83], v100 offset:448
	s_waitcnt lgkmcnt(8)
	v_mfma_f32_16x16x32_bf16 v[60:63], v[84:87], v[28:31], v[60:63]
	s_waitcnt lgkmcnt(1)
	v_pk_mul_f32 v[14:15], v[14:15], v[72:73]
	v_pk_mul_f32 v[12:13], v[12:13], v[70:71]
	v_pk_mul_f32 v[10:11], v[10:11], v[72:73]
	s_waitcnt lgkmcnt(0)
	v_pk_mul_f32 v[6:7], v[6:7], v[82:83]
	v_pk_mul_f32 v[4:5], v[4:5], v[80:81]
	v_mfma_f32_16x16x32_bf16 v[36:39], v[84:87], v[20:23], v[36:39]
	v_mul_f32_e64 v8, v8, v70
	v_mul_f32_e64 v9, v9, v71
	v_pk_mul_f32 v[2:3], v[2:3], v[82:83]
	v_pk_mul_f32 v[0:1], v[0:1], v[80:81]
	v_mfma_f32_16x16x32_bf16 v[24:27], v[88:91], v[28:31], v[24:27]
	s_mov_b32 s9, 0
	v_cmp_gt_i32_e32 vcc, 32, v114
	v_mfma_f32_16x16x32_bf16 v[16:19], v[88:91], v[20:23], v[16:19]
	ds_read_b64_tr_b16 v[84:85], v116 offset:53248
	ds_read_b64_tr_b16 v[86:87], v116 offset:55424
	ds_read_b64_tr_b16 v[90:91], v116 offset:55456
	ds_read_b64_tr_b16 v[88:89], v116 offset:53280
	v_mfma_f32_16x16x32_bf16 v[12:15], v[92:95], v[28:31], v[12:15]
	v_mfma_f32_16x16x32_bf16 v[4:7], v[96:99], v[28:31], v[4:7]
	ds_read_b64_tr_b16 v[28:29], v115 offset:9216
	ds_read_b64_tr_b16 v[30:31], v115 offset:10368
	v_mfma_f32_16x16x32_bf16 v[8:11], v[92:95], v[20:23], v[8:11]
	v_mfma_f32_16x16x32_bf16 v[0:3], v[96:99], v[20:23], v[0:3]
	ds_read_b64_tr_b16 v[20:21], v115 offset:9248
	ds_read_b64_tr_b16 v[70:71], v115 offset:9280
	ds_read_b64_tr_b16 v[80:81], v115 offset:9312
	ds_read_b64_tr_b16 v[22:23], v115 offset:10400
	ds_read_b64_tr_b16 v[72:73], v115 offset:10432
	ds_read_b64_tr_b16 v[82:83], v115 offset:10464
	s_waitcnt lgkmcnt(6)
	v_mfma_f32_16x16x32_bf16 v[44:47], v[28:31], v[84:87], v[44:47]
	v_mfma_f32_16x16x32_bf16 v[28:31], v[28:31], v[88:91], v[32:35]
	s_waitcnt lgkmcnt(2)
	v_mfma_f32_16x16x32_bf16 v[32:35], v[20:23], v[84:87], v[76:79]
	v_mfma_f32_16x16x32_bf16 v[20:23], v[20:23], v[88:91], v[40:43]
	s_waitcnt lgkmcnt(1)
	v_mfma_f32_16x16x32_bf16 v[40:43], v[70:73], v[84:87], v[66:69]
	ds_read_b64_tr_b16 v[64:65], v115 offset:9344
	s_nop 1
	ds_read_b64_tr_b16 v[66:67], v115 offset:10496
	s_waitcnt lgkmcnt(0)
	v_mfma_f32_16x16x32_bf16 v[60:63], v[64:67], v[84:87], v[60:63]
	v_mfma_f32_16x16x32_bf16 v[36:39], v[64:67], v[88:91], v[36:39]
	v_lshlrev_b32_e32 v64, 4, v114
	v_mfma_f32_16x16x32_bf16 v[48:51], v[70:73], v[88:91], v[48:51]
	ds_read_b64_tr_b16 v[68:69], v115 offset:9376
	ds_read_b64_tr_b16 v[72:73], v115 offset:9408
	ds_read_b64_tr_b16 v[76:77], v115 offset:9440
	ds_read_b64_tr_b16 v[70:71], v115 offset:10528
	ds_read_b64_tr_b16 v[74:75], v115 offset:10560
	ds_read_b64_tr_b16 v[78:79], v115 offset:10592
	s_waitcnt lgkmcnt(0)
	s_barrier
; template <bool FULL>
; __device__ __forceinline__ void gla_pass(const Params& P, LAS unsigned char* lds, f32x4 (&S)[8][2], int bh, int c0, int L, bool dry) {
;     ...
;             for (int kt = 0; kt < 8; ++kt) { const bf16x8 ak = trfrag(Lks, KS_P, 32 * k2, 32 * kt, g, fr);
;                 S[kt][0] = __builtin_amdgcn_mfma_f32_16x16x32_bf16(ak, vf[0][k2], S[kt][0], 0, 0, 0); S[kt][1] = __builtin_amdgcn_mfma_f32_16x16x32_bf16(ak, vf[1][k2], S[kt][1], 0, 0, 0); }
; __device__ __forceinline__ void gla_scan(const Params& P, LAS unsigned char* lds, int bh, int seg, int nseg, bool dry) {
;     ...
;         char* dst = (char*)(SL + (size_t)(bh * 3 + seg) * 32768);
; #pragma unroll
;         for (int kt = 0; kt < 8; ++kt)
; #pragma unroll
;             for (int vt = 0; vt < 2; ++vt) *(f32x4*)(dst + (size_t)((unsigned)tid * 16u + (unsigned)((kt * 2 + vt) * 8192))) = S[kt][vt];
;         if (tid < 32) {
;             f32x4 dc = (f32x4){1.f, 1.f, 1.f, 1.f};
;             for (int n = c0; n < c0 + L; ++n) dc = dc * *(const f32x4*)(DEC + (size_t)(bh * 64 + n) * 128 + 4 * tid);
;             *(f32x4*)(DL + (size_t)(bh * 4 + seg) * 128 + 4 * tid) = dc;
;         }
;         asm volatile("s_waitcnt vmcnt(0)" ::: "memory");
;         __syncthreads();
;         if (tid == 0) { __builtin_amdgcn_fence(__ATOMIC_RELEASE, "agent"); asm volatile("s_waitcnt vmcnt(0)" ::: "memory");
;             __hip_atomic_store(FL + (bh * 4 + seg) * 16, 1u, __ATOMIC_RELAXED, __HIP_MEMORY_SCOPE_AGENT); }
	s_barrier
	global_store_dwordx4 v64, v[44:47], s[4:5] sc1
	v_mfma_f32_16x16x32_bf16 v[52:55], v[80:83], v[84:87], v[52:55]
	s_nop 0
	v_add_u32_e32 v44, 0x2000, v64
	global_store_dwordx4 v44, v[28:31], s[4:5] sc1
	v_mfma_f32_16x16x32_bf16 v[56:59], v[80:83], v[88:91], v[56:59]
	s_nop 0
	v_add_u32_e32 v28, 0x4000, v64
	global_store_dwordx4 v28, v[32:35], s[4:5] sc1
	v_add_u32_e32 v28, 0x6000, v64
	global_store_dwordx4 v28, v[20:23], s[4:5] sc1
	v_mfma_f32_16x16x32_bf16 v[24:27], v[68:71], v[84:87], v[24:27]
	s_nop 0
	v_add_u32_e32 v20, 0x8000, v64
	global_store_dwordx4 v20, v[40:43], s[4:5] sc1
	v_add_u32_e32 v20, 0xa000, v64
	global_store_dwordx4 v20, v[48:51], s[4:5] sc1
	v_add_u32_e32 v20, 0xc000, v64
	global_store_dwordx4 v20, v[52:55], s[4:5] sc1
	v_add_u32_e32 v20, 0xe000, v64
	v_mfma_f32_16x16x32_bf16 v[16:19], v[68:71], v[88:91], v[16:19]
	global_store_dwordx4 v20, v[56:59], s[4:5] sc1
	v_add_u32_e32 v20, 0x10000, v64
	global_store_dwordx4 v20, v[60:63], s[4:5] sc1
	v_mfma_f32_16x16x32_bf16 v[12:15], v[72:75], v[84:87], v[12:15]
	v_add_u32_e32 v20, 0x12000, v64
	global_store_dwordx4 v20, v[36:39], s[4:5] sc1
	v_add_u32_e32 v20, 0x14000, v64
	v_mfma_f32_16x16x32_bf16 v[8:11], v[72:75], v[88:91], v[8:11]
	global_store_dwordx4 v20, v[24:27], s[4:5] sc1
	v_add_u32_e32 v20, 0x16000, v64
	global_store_dwordx4 v20, v[16:19], s[4:5] sc1
	v_mfma_f32_16x16x32_bf16 v[4:7], v[76:79], v[84:87], v[4:7]
	s_nop 0
	v_add_u32_e32 v16, 0x18000, v64
	global_store_dwordx4 v16, v[12:15], s[4:5] sc1
	v_mfma_f32_16x16x32_bf16 v[0:3], v[76:79], v[88:91], v[0:3]
	s_nop 0
	v_add_u32_e32 v12, 0x1a000, v64
	global_store_dwordx4 v12, v[8:11], s[4:5] sc1
	s_nop 1
	v_add_u32_e32 v8, 0x1c000, v64
	global_store_dwordx4 v8, v[4:7], s[4:5] sc1
	s_nop 1
	v_add_u32_e32 v4, 0x1e000, v64
	global_store_dwordx4 v4, v[0:3], s[4:5] sc1
	s_and_saveexec_b64 s[4:5], vcc
	s_cbranch_execz .LBB0_670
	v_lshlrev_b32_e32 v0, 2, v114
	v_ashrrev_i32_e32 v1, 31, v0
	v_lshlrev_b64 v[64:65], 2, v[0:1]
	s_or_b32 s8, s0, s22
	v_lshl_add_u64 v[0:1], s[50:51], 0, v[64:65]
	s_lshl_b32 s8, s8, 9
	v_lshl_add_u64 v[32:33], v[0:1], 0, s[8:9]
	global_load_dwordx4 v[0:3], v[32:33], off
	global_load_dwordx4 v[4:7], v[32:33], off offset:512
	global_load_dwordx4 v[8:11], v[32:33], off offset:1024
	global_load_dwordx4 v[12:15], v[32:33], off offset:1536
	global_load_dwordx4 v[16:19], v[32:33], off offset:2048
	global_load_dwordx4 v[20:23], v[32:33], off offset:2560
	global_load_dwordx4 v[24:27], v[32:33], off offset:3072
	global_load_dwordx4 v[28:31], v[32:33], off offset:3584
	s_movk_i32 s8, 0x1000
	v_add_co_u32_e32 v66, vcc, s8, v32
	s_lshl_b32 s8, s1, 11
	s_nop 0
	v_addc_co_u32_e32 v67, vcc, 0, v33, vcc
	global_load_dwordx4 v[32:35], v[66:67], off
	global_load_dwordx4 v[36:39], v[66:67], off offset:512
	global_load_dwordx4 v[40:43], v[66:67], off offset:1024
	global_load_dwordx4 v[44:47], v[66:67], off offset:1536
	global_load_dwordx4 v[48:51], v[66:67], off offset:2048
	global_load_dwordx4 v[52:55], v[66:67], off offset:2560
	global_load_dwordx4 v[56:59], v[66:67], off offset:3072
	global_load_dwordx4 v[60:63], v[66:67], off offset:3584
	s_lshl_b32 s9, s3, 9
	s_or_b32 s8, s8, s9
	s_add_u32 s8, s6, s8
	s_addc_u32 s9, s7, 0
	s_waitcnt vmcnt(14)
	v_pk_mul_f32 v[2:3], v[2:3], v[6:7]
	v_pk_mul_f32 v[0:1], v[0:1], v[4:5]
	s_waitcnt vmcnt(13)
	v_pk_mul_f32 v[2:3], v[2:3], v[10:11]
	v_pk_mul_f32 v[0:1], v[0:1], v[8:9]
	s_waitcnt vmcnt(12)
	v_pk_mul_f32 v[2:3], v[2:3], v[14:15]
	v_pk_mul_f32 v[0:1], v[0:1], v[12:13]
	s_waitcnt vmcnt(11)
	v_pk_mul_f32 v[2:3], v[2:3], v[18:19]
	v_pk_mul_f32 v[0:1], v[0:1], v[16:17]
	s_waitcnt vmcnt(10)
	v_pk_mul_f32 v[2:3], v[2:3], v[22:23]
	v_pk_mul_f32 v[0:1], v[0:1], v[20:21]
	s_waitcnt vmcnt(9)
	v_pk_mul_f32 v[2:3], v[2:3], v[26:27]
	v_pk_mul_f32 v[0:1], v[0:1], v[24:25]
	s_waitcnt vmcnt(8)
	v_pk_mul_f32 v[2:3], v[2:3], v[30:31]
	v_pk_mul_f32 v[0:1], v[0:1], v[28:29]
	s_waitcnt vmcnt(7)
	v_pk_mul_f32 v[2:3], v[2:3], v[34:35]
	v_pk_mul_f32 v[0:1], v[0:1], v[32:33]
	s_waitcnt vmcnt(6)
	v_pk_mul_f32 v[2:3], v[2:3], v[38:39]
	v_pk_mul_f32 v[0:1], v[0:1], v[36:37]
	s_waitcnt vmcnt(5)
	v_pk_mul_f32 v[2:3], v[2:3], v[42:43]
	v_pk_mul_f32 v[0:1], v[0:1], v[40:41]
	s_waitcnt vmcnt(4)
	v_pk_mul_f32 v[2:3], v[2:3], v[46:47]
	v_pk_mul_f32 v[0:1], v[0:1], v[44:45]
	s_waitcnt vmcnt(3)
	v_pk_mul_f32 v[2:3], v[2:3], v[50:51]
	v_pk_mul_f32 v[0:1], v[0:1], v[48:49]
	s_waitcnt vmcnt(2)
	v_pk_mul_f32 v[2:3], v[2:3], v[54:55]
	v_pk_mul_f32 v[0:1], v[0:1], v[52:53]
	s_waitcnt vmcnt(1)
	v_pk_mul_f32 v[2:3], v[2:3], v[58:59]
	v_pk_mul_f32 v[0:1], v[0:1], v[56:57]
	s_waitcnt vmcnt(0)
	v_pk_mul_f32 v[2:3], v[2:3], v[62:63]
	v_pk_mul_f32 v[0:1], v[0:1], v[60:61]
	v_lshl_add_u64 v[4:5], s[8:9], 0, v[64:65]
	global_store_dwordx4 v[4:5], v[0:3], off sc1
.LBB0_670:
	s_or_b64 exec, exec, s[4:5]
	s_waitcnt vmcnt(0)
	v_cmp_eq_u32_e32 vcc, 0, v114
	s_barrier
	s_and_saveexec_b64 s[4:5], vcc
	s_cbranch_execz .LBB0_672
	s_or_b32 s8, s0, s22
	s_mov_b32 s9, 0
	s_lshl_b64 s[8:9], s[8:9], 2
	s_waitcnt vmcnt(0)
	s_waitcnt vmcnt(0)
	s_add_u32 s8, s20, s8
	s_addc_u32 s9, s21, s9
	v_mov_b32_e32 v0, 0
	v_mov_b32_e32 v1, 1
	global_store_dword v0, v1, s[8:9] sc1
